# MLA attention loop: s_setprio 2 for its first 24 of 68 K/V tiles only (then 0)
# baseline (speedup 1.0000x reference)
.LBB0_121:
	s_lshl_b32 s28, s24, 8
	s_lshl_b32 s0, s25, 7
	s_add_i32 s0, s0, s28
	s_cmp_lt_u32 s24, 4
	s_cselect_b32 s41, 4, 0x44
	s_andn2_b64 vcc, exec, s[30:31]
	s_mov_b64 s[30:31], -1
	s_cbranch_vccz .LBB0_125
	s_mul_i32 s25, s0, 0x600
	v_readlane_b32 s30, v253, 3
	s_mul_hi_i32 s1, s0, 0x600
	v_readlane_b32 s31, v253, 4
	s_add_u32 s25, s30, s25
	s_mul_i32 s30, s40, 0x60
	s_addc_u32 s1, s31, s1
	s_ashr_i32 s31, s30, 31
	s_lshl_b64 s[30:31], s[30:31], 1
	s_add_u32 s42, s25, s30
	s_addc_u32 s43, s1, s31
	s_mul_i32 s25, s28, 0x600
	v_readlane_b32 s26, v253, 5
	s_mul_hi_u32 s1, s28, 0x600
	s_add_u32 s25, s26, s25
	v_readlane_b32 s26, v253, 6
	s_addc_u32 s1, s26, s1
	s_add_u32 s36, s25, s30
	s_addc_u32 s37, s1, s31
	s_lshl_b64 s[30:31], s[28:29], 11
	s_add_u32 s1, s82, s30
	s_addc_u32 s25, s83, s31
	s_lshl_b32 s30, s40, 6
	s_ashr_i32 s31, s30, 31
	s_lshl_b64 s[30:31], s[30:31], 1
	v_mov_b32_e32 v74, v208
	v_mov_b32_e32 v75, v208
	s_add_u32 s1, s1, s30
	v_mov_b32_e32 v26, v208
	s_addc_u32 s25, s25, s31
	s_add_u32 s38, s1, 0x9f54400
	v_ashrrev_i32_e32 v25, 6, v26
	v_and_b32_e32 v27, 15, v26
	v_and_b32_e32 v128, 48, v26
	v_lshl_or_b32 v12, v25, 5, v27
	v_lshl_add_u64 v[8:9], s[42:43], 0, v[128:129]
	s_movk_i32 s1, 0x600
	v_mad_i64_i32 v[10:11], s[42:43], v12, s1, v[8:9]
	v_or_b32_e32 v12, 16, v12
	v_mad_i64_i32 v[20:21], s[42:43], v12, s1, v[8:9]
	s_mov_b32 s1, 0x2aaaaaab
	v_mul_hi_i32 v29, v26, s1
	v_lshrrev_b32_e32 v30, 31, v29
	v_ashrrev_i32_e32 v29, 1, v29
	v_and_b32_e32 v28, 0xffffffc0, v26
	v_add_u32_e32 v29, v29, v30
	v_and_b32_e32 v24, 63, v26
	v_mul_lo_u32 v30, v29, 12
	v_add_u32_e32 v28, 0x100, v28
	v_sub_u32_e32 v30, v26, v30
	v_lshrrev_b32_e32 v31, 2, v29
	v_or_b32_e32 v24, v28, v24
	v_bitop3_b32 v30, v31, v30, 3 bitop3:0x6c
	v_mul_hi_i32 v31, v24, s1
	v_lshrrev_b32_e32 v32, 31, v31
	v_ashrrev_i32_e32 v31, 1, v31
	v_add_u32_e32 v31, v31, v32
	v_mul_lo_u32 v32, v31, 12
	v_sub_u32_e32 v32, v24, v32
	v_lshrrev_b32_e32 v33, 2, v31
	v_bitop3_b32 v32, v33, v32, 3 bitop3:0x6c
	v_bitop3_b32 v33, v26, 63, v213 bitop3:0xe0
	v_add_u32_e32 v33, 0x200, v33
	v_mul_hi_i32 v34, v33, s1
	v_lshrrev_b32_e32 v35, 31, v34
	v_ashrrev_i32_e32 v34, 1, v34
	v_add_u32_e32 v34, v34, v35
	v_mul_lo_u32 v35, v34, 12
	v_sub_u32_e32 v33, v33, v35
	v_lshrrev_b32_e32 v35, 2, v34
	v_bitop3_b32 v33, v35, v33, 3 bitop3:0x6c
	v_ashrrev_i32_e32 v35, 31, v26
	v_lshrrev_b32_e32 v35, 29, v35
	v_add_u32_e32 v35, v26, v35
	v_ashrrev_i32_e32 v28, 31, v28
	v_ashrrev_i32_e32 v36, 3, v35
	v_and_b32_e32 v35, 0x1ffffff8, v35
	v_lshrrev_b32_e32 v28, 29, v28
	v_sub_u32_e32 v35, v26, v35
	v_lshrrev_b32_e32 v37, 1, v36
	v_add_u32_e32 v28, v24, v28
	v_bitop3_b32 v35, v37, v35, 7 bitop3:0x6c
	v_ashrrev_i32_e32 v37, 3, v28
	v_and_b32_e32 v28, 0x1ffffff8, v28
	v_sub_u32_e32 v24, v24, v28
	v_lshrrev_b32_e32 v28, 1, v37
	v_bitop3_b32 v24, v28, v24, 7 bitop3:0x6c
	v_lshlrev_b32_e32 v28, 10, v37
	s_movk_i32 s1, 0x300
	v_lshl_add_u32 v64, v24, 3, v28
	v_mul_lo_u32 v24, v29, s1
	v_lshl_add_u32 v66, v30, 3, v24
	v_mul_lo_u32 v24, v31, s1
	v_lshl_add_u32 v68, v32, 3, v24
	v_mul_lo_u32 v24, v34, s1
	v_lshlrev_b32_e32 v76, 10, v25
	v_lshl_add_u32 v70, v33, 3, v24
	v_lshlrev_b32_e32 v24, 10, v36
	v_ashrrev_i32_e32 v67, 31, v66
	v_readfirstlane_b32 s1, v76
	v_add_u32_e32 v28, 0x1000, v76
	global_load_dwordx4 v[0:3], v[10:11], off
	global_load_dwordx4 v[4:7], v[10:11], off offset:64
	s_nop 0
	global_load_dwordx4 v[8:11], v[10:11], off offset:128
	s_nop 0
	global_load_dwordx4 v[12:15], v[20:21], off
	global_load_dwordx4 v[16:19], v[20:21], off offset:64
	s_nop 0
	global_load_dwordx4 v[20:23], v[20:21], off offset:128
	v_lshl_add_u32 v72, v35, 3, v24
	s_waitcnt lgkmcnt(0)
	s_barrier
	v_lshl_add_u64 v[24:25], v[66:67], 1, s[36:37]
	s_mov_b32 m0, s1
	v_ashrrev_i32_e32 v69, 31, v68
	v_readfirstlane_b32 s1, v28
	v_add_u32_e32 v28, 0x2000, v76
	global_load_lds_dwordx4 v[24:25], off
	v_lshl_add_u64 v[24:25], v[68:69], 1, s[36:37]
	s_mov_b32 m0, s1
	v_ashrrev_i32_e32 v71, 31, v70
	v_readfirstlane_b32 s1, v28
	v_add_u32_e32 v28, 0x3000, v76
	s_addc_u32 s39, s25, 0
	global_load_lds_dwordx4 v[24:25], off
	v_lshl_add_u64 v[24:25], v[70:71], 1, s[36:37]
	s_mov_b32 m0, s1
	v_ashrrev_i32_e32 v73, 31, v72
	v_readfirstlane_b32 s1, v28
	v_add_u32_e32 v28, 0x4000, v76
	global_load_lds_dwordx4 v[24:25], off
	v_lshl_add_u64 v[24:25], v[72:73], 1, s[38:39]
	s_mov_b32 m0, s1
	v_ashrrev_i32_e32 v65, 31, v64
	v_readfirstlane_b32 s1, v28
	global_load_lds_dwordx4 v[24:25], off
	v_lshl_add_u64 v[24:25], v[64:65], 1, s[38:39]
	s_mov_b32 m0, s1
	v_bfe_u32 v29, v26, 1, 1
	global_load_lds_dwordx4 v[24:25], off
	v_bfe_u32 v24, v26, 4, 2
	v_bfe_u32 v25, v26, 2, 2
	v_xor_b32_e32 v28, v24, v25
	v_lshlrev_b32_e32 v25, 7, v25
	v_lshlrev_b32_e32 v30, 1, v24
	v_lshl_or_b32 v24, v24, 9, v25
	v_lshlrev_b32_e32 v25, 3, v26
	v_bfe_u32 v31, v26, 3, 1
	v_and_b32_e32 v25, 8, v25
	s_movk_i32 s1, 0x3000
	v_or3_b32 v24, v24, v25, s1
	v_bitop3_b32 v25, v30, v29, v31 bitop3:0x36
	v_lshl_or_b32 v77, v25, 4, v24
	v_or_b32_e32 v25, 2, v29
	v_bitop3_b32 v25, v30, v25, v31 bitop3:0x36
	v_lshl_or_b32 v78, v25, 4, v24
	v_or_b32_e32 v25, 4, v29
	v_bitop3_b32 v25, v30, v25, v31 bitop3:0x36
	v_lshl_or_b32 v79, v25, 4, v24
	v_or_b32_e32 v25, 6, v29
	v_bitop3_b32 v25, v30, v25, v31 bitop3:0x36
	v_lshl_or_b32 v80, v25, 4, v24
	v_mul_u32_u24_e32 v24, 0xc0, v27
	v_lshl_or_b32 v81, v28, 4, v24
	v_mov_b32_e32 v24, 0
	v_readlane_b32 s48, v255, 3
	s_mov_b32 s25, 0
	v_mov_b32_e32 v25, v24
	v_mov_b32_e32 v26, v24
	v_mov_b32_e32 v27, v24
	v_mov_b32_e32 v40, v24
	v_mov_b32_e32 v41, v24
	v_mov_b32_e32 v42, v24
	v_mov_b32_e32 v43, v24
	v_mov_b32_e32 v28, v24
	v_mov_b32_e32 v29, v24
	v_mov_b32_e32 v30, v24
	v_mov_b32_e32 v31, v24
	v_mov_b32_e32 v48, v24
	v_mov_b32_e32 v49, v24
	v_mov_b32_e32 v50, v24
	v_mov_b32_e32 v51, v24
	v_mov_b32_e32 v32, v24
	v_mov_b32_e32 v33, v24
	v_mov_b32_e32 v34, v24
	v_mov_b32_e32 v35, v24
	v_mov_b32_e32 v56, v24
	v_mov_b32_e32 v57, v24
	v_mov_b32_e32 v58, v24
	v_mov_b32_e32 v59, v24
	v_mov_b32_e32 v44, v24
	v_mov_b32_e32 v45, v24
	v_mov_b32_e32 v46, v24
	v_mov_b32_e32 v47, v24
	v_mov_b32_e32 v60, v24
	v_mov_b32_e32 v61, v24
	v_mov_b32_e32 v62, v24
	v_mov_b32_e32 v63, v24
	v_mov_b32_e32 v52, v24
	v_mov_b32_e32 v53, v24
	v_mov_b32_e32 v54, v24
	v_mov_b32_e32 v55, v24
	v_mov_b32_e32 v36, v24
	v_mov_b32_e32 v37, v24
	v_mov_b32_e32 v38, v24
	v_mov_b32_e32 v39, v24
	v_readlane_b32 s49, v255, 4
	v_readlane_b32 s50, v255, 5
	v_readlane_b32 s51, v255, 6
	s_waitcnt vmcnt(0)
	s_setprio 2
.LBB0_123:
	s_cmp_lg_u32 s25, 24
	s_cbranch_scc1 .Lmla_pk
	s_setprio 0
.Lmla_pk:
	s_bitcmp1_b32 s25, 0
	s_cselect_b32 s26, 0x5000, 0
	s_add_i32 s1, s25, 1
	s_cmp_lt_u32 s1, s41
	s_cselect_b32 s28, s1, s25
	s_mul_i32 s42, s28, 0x18000
	s_mul_hi_u32 s25, s28, 0x18000
	s_add_u32 s42, s36, s42
	s_addc_u32 s43, s37, s25
	s_lshl_b64 s[44:45], s[28:29], 17
	s_add_u32 s44, s38, s44
	s_addc_u32 s45, s39, s45
	s_bitcmp1_b32 s1, 0
	s_cselect_b32 s25, 0x5000, 0
	s_waitcnt vmcnt(0)
	v_add_u32_e32 v128, s25, v76
	s_waitcnt lgkmcnt(0)
	s_barrier
	v_or_b32_e32 v126, s26, v81
	v_readfirstlane_b32 s25, v128
	v_add_u32_e32 v131, 0x1000, v128
	ds_read_b128 v[82:85], v126 offset:0
	ds_read_b128 v[86:89], v126 offset:3072
	ds_read_b128 v[90:93], v126 offset:6144
	ds_read_b128 v[94:97], v126 offset:9216
	ds_read_b128 v[98:101], v126 offset:64
	ds_read_b128 v[102:105], v126 offset:3136
	ds_read_b128 v[106:109], v126 offset:6208
	ds_read_b128 v[110:113], v126 offset:9280
	ds_read_b128 v[114:117], v126 offset:128
	ds_read_b128 v[118:121], v126 offset:3200
	ds_read_b128 v[122:125], v126 offset:6272
	ds_read_b128 v[134:137], v126 offset:9344
	v_lshl_add_u64 v[126:127], v[66:67], 1, s[42:43]
	v_add_u32_e32 v133, 0x2000, v128
	v_readfirstlane_b32 s28, v131
	s_mov_b32 m0, s25
	v_lshl_add_u64 v[138:139], v[68:69], 1, s[42:43]
	v_lshl_add_u64 v[140:141], v[70:71], 1, s[42:43]
	v_add_u32_e32 v146, 0x3000, v128
	v_readfirstlane_b32 s42, v133
	global_load_lds_dwordx4 v[126:127], off
	s_mov_b32 m0, s28
	v_add_u32_e32 v128, 0x4000, v128
	v_readfirstlane_b32 s43, v146
	global_load_lds_dwordx4 v[138:139], off
	s_mov_b32 m0, s42
	v_lshl_add_u64 v[142:143], v[72:73], 1, s[44:45]
	v_lshl_add_u64 v[144:145], v[64:65], 1, s[44:45]
	v_readfirstlane_b32 s44, v128
	global_load_lds_dwordx4 v[140:141], off
	s_mov_b32 m0, s43
	v_add_u32_e32 v126, s26, v77
	global_load_lds_dwordx4 v[142:143], off
	s_mov_b32 m0, s44
	v_add_u32_e32 v127, s26, v78
	global_load_lds_dwordx4 v[144:145], off
	s_waitcnt lgkmcnt(8)
	v_add_u32_e32 v128, s26, v79
	v_mfma_f32_16x16x32_bf16 v[138:141], v[82:85], v[0:3], 0
	v_add_u32_e32 v131, s26, v80
	s_cmp_lg_u32 s41, s1
	s_mov_b32 s25, s1
	v_mfma_f32_16x16x32_bf16 v[82:85], v[82:85], v[12:15], 0
	v_mfma_f32_16x16x32_bf16 v[142:145], v[86:89], v[0:3], 0
	v_mfma_f32_16x16x32_bf16 v[86:89], v[86:89], v[12:15], 0
	v_mfma_f32_16x16x32_bf16 v[146:149], v[90:93], v[0:3], 0
	v_mfma_f32_16x16x32_bf16 v[90:93], v[90:93], v[12:15], 0
	s_waitcnt lgkmcnt(4)
	v_mfma_f32_16x16x32_bf16 v[150:153], v[94:97], v[0:3], 0
	v_mfma_f32_16x16x32_bf16 v[94:97], v[94:97], v[12:15], 0
	v_mfma_f32_16x16x32_bf16 v[138:141], v[98:101], v[4:7], v[138:141]
	v_mfma_f32_16x16x32_bf16 v[82:85], v[98:101], v[16:19], v[82:85]
	v_mfma_f32_16x16x32_bf16 v[98:101], v[102:105], v[4:7], v[142:145]
	v_mfma_f32_16x16x32_bf16 v[86:89], v[102:105], v[16:19], v[86:89]
	v_mfma_f32_16x16x32_bf16 v[90:93], v[106:109], v[16:19], v[90:93]
	s_waitcnt lgkmcnt(0)
	v_mfma_f32_16x16x32_bf16 v[102:105], v[106:109], v[4:7], v[146:149]
	v_mfma_f32_16x16x32_bf16 v[106:109], v[110:113], v[4:7], v[150:153]
	v_mfma_f32_16x16x32_bf16 v[94:97], v[110:113], v[16:19], v[94:97]
	v_mfma_f32_16x16x32_bf16 v[82:85], v[114:117], v[20:23], v[82:85]
	v_mfma_f32_16x16x32_bf16 v[98:101], v[118:121], v[8:11], v[98:101]
	v_mfma_f32_16x16x32_bf16 v[86:89], v[118:121], v[20:23], v[86:89]
	s_nop 5
	v_exp_f32_e32 v133, v82
	v_mfma_f32_16x16x32_bf16 v[106:109], v[134:137], v[8:11], v[106:109]
	v_mfma_f32_16x16x32_bf16 v[94:97], v[134:137], v[20:23], v[94:97]
	v_exp_f32_e32 v135, v84
	v_exp_f32_e32 v136, v85
	v_exp_f32_e32 v84, v98
	v_exp_f32_e32 v85, v99
	v_exp_f32_e32 v98, v100
	v_exp_f32_e32 v99, v101
	v_exp_f32_e32 v100, v86
	v_exp_f32_e32 v101, v87
	v_mfma_f32_16x16x32_bf16 v[110:113], v[114:117], v[8:11], v[138:141]
	v_exp_f32_e32 v137, v88
	v_cvt_pk_bf16_f32 v84, v84, v85
	v_cvt_pk_bf16_f32 v85, v98, v99
	v_cvt_pk_bf16_f32 v88, v100, v101
	v_mov_b64_e32 v[100:101], s[50:51]
	v_mfma_f32_16x16x32_bf16 v[102:105], v[122:125], v[8:11], v[102:105]
	s_nop 1
	v_exp_f32_e32 v110, v110
	v_exp_f32_e32 v111, v111
	v_exp_f32_e32 v112, v112
	v_mfma_f32_16x16x32_bf16 v[90:93], v[122:125], v[20:23], v[90:93]
	v_exp_f32_e32 v113, v113
	v_exp_f32_e32 v134, v83
	v_exp_f32_e32 v89, v89
	v_mov_b64_e32 v[98:99], s[48:49]
	ds_read_b64_tr_b16 v[138:139], v126 offset:0
	ds_read_b64_tr_b16 v[140:141], v126 offset:2048
	ds_read_b64_tr_b16 v[122:123], v127 offset:0
	ds_read_b64_tr_b16 v[124:125], v127 offset:2048
	ds_read_b64_tr_b16 v[118:119], v128 offset:0
	ds_read_b64_tr_b16 v[120:121], v128 offset:2048
	ds_read_b64_tr_b16 v[114:115], v131 offset:0
	ds_read_b64_tr_b16 v[116:117], v131 offset:2048
	v_cvt_pk_bf16_f32 v82, v110, v111
	v_cvt_pk_bf16_f32 v83, v112, v113
	v_cvt_pk_bf16_f32 v86, v133, v134
	v_cvt_pk_bf16_f32 v87, v135, v136
	v_cvt_pk_bf16_f32 v89, v137, v89
	v_exp_f32_e32 v102, v102
	v_exp_f32_e32 v103, v103
	v_exp_f32_e32 v104, v104
	v_exp_f32_e32 v105, v105
	v_exp_f32_e32 v90, v90
	v_exp_f32_e32 v91, v91
	v_exp_f32_e32 v92, v92
	v_exp_f32_e32 v93, v93
	v_exp_f32_e32 v106, v106
	v_exp_f32_e32 v107, v107
	v_exp_f32_e32 v108, v108
	v_exp_f32_e32 v109, v109
	v_exp_f32_e32 v94, v94
	v_exp_f32_e32 v95, v95
	v_exp_f32_e32 v96, v96
	v_exp_f32_e32 v97, v97
	s_waitcnt lgkmcnt(0)
	v_mfma_f32_16x16x32_bf16 v[52:55], v[98:101], v[82:85], v[52:55]
	v_mfma_f32_16x16x32_bf16 v[44:47], v[138:141], v[86:89], v[44:47]
	v_mfma_f32_16x16x32_bf16 v[56:59], v[122:125], v[82:85], v[56:59]
	v_mfma_f32_16x16x32_bf16 v[32:35], v[122:125], v[86:89], v[32:35]
	v_mfma_f32_16x16x32_bf16 v[48:51], v[118:121], v[82:85], v[48:51]
	v_mfma_f32_16x16x32_bf16 v[28:31], v[118:121], v[86:89], v[28:31]
	v_mfma_f32_16x16x32_bf16 v[40:43], v[114:117], v[82:85], v[40:43]
	v_mfma_f32_16x16x32_bf16 v[24:27], v[114:117], v[86:89], v[24:27]
	v_mfma_f32_16x16x32_bf16 v[36:39], v[98:101], v[86:89], v[36:39]
	v_cvt_pk_bf16_f32 v86, v90, v91
	v_cvt_pk_bf16_f32 v87, v92, v93
	v_cvt_pk_bf16_f32 v88, v94, v95
	v_mfma_f32_16x16x32_bf16 v[60:63], v[138:141], v[82:85], v[60:63]
	ds_read_b64_tr_b16 v[142:143], v126 offset:4096
	ds_read_b64_tr_b16 v[144:145], v126 offset:6144
	ds_read_b64_tr_b16 v[138:139], v127 offset:4096
	ds_read_b64_tr_b16 v[140:141], v127 offset:6144
	ds_read_b64_tr_b16 v[134:135], v128 offset:4096
	ds_read_b64_tr_b16 v[136:137], v128 offset:6144
	ds_read_b64_tr_b16 v[110:111], v131 offset:4096
	ds_read_b64_tr_b16 v[112:113], v131 offset:6144
	v_cvt_pk_bf16_f32 v82, v102, v103
	v_cvt_pk_bf16_f32 v83, v104, v105
	v_cvt_pk_bf16_f32 v84, v106, v107
	v_cvt_pk_bf16_f32 v85, v108, v109
	v_cvt_pk_bf16_f32 v89, v96, v97
	s_waitcnt lgkmcnt(0)
	s_nop 0
	v_mfma_f32_16x16x32_bf16 v[52:55], v[98:101], v[82:85], v[52:55]
	v_mfma_f32_16x16x32_bf16 v[36:39], v[98:101], v[86:89], v[36:39]
	v_mfma_f32_16x16x32_bf16 v[60:63], v[142:145], v[82:85], v[60:63]
	v_mfma_f32_16x16x32_bf16 v[44:47], v[142:145], v[86:89], v[44:47]
	v_mfma_f32_16x16x32_bf16 v[56:59], v[138:141], v[82:85], v[56:59]
	v_mfma_f32_16x16x32_bf16 v[32:35], v[138:141], v[86:89], v[32:35]
	v_mfma_f32_16x16x32_bf16 v[48:51], v[134:137], v[82:85], v[48:51]
	v_mfma_f32_16x16x32_bf16 v[28:31], v[134:137], v[86:89], v[28:31]
	v_mfma_f32_16x16x32_bf16 v[40:43], v[110:113], v[82:85], v[40:43]
	v_mfma_f32_16x16x32_bf16 v[24:27], v[110:113], v[86:89], v[24:27]
	s_cbranch_scc1 .LBB0_123
	s_setprio 0
	v_div_scale_f32 v1, s[36:37], v52, v52, 1.0
	v_rcp_f32_e32 v2, v1
	v_ashrrev_i32_e32 v0, 1, v75
	v_and_b32_e32 v0, 0xffffffe0, v0
	v_add_u32_e32 v0, s0, v0
	v_and_or_b32 v12, v74, 15, v0
	v_fma_f32 v0, -v1, v2, 1.0
	v_fmac_f32_e32 v2, v0, v2
	v_div_scale_f32 v0, vcc, 1.0, v52, 1.0
	v_mul_f32_e32 v3, v0, v2
	v_fma_f32 v4, -v1, v3, v0
	v_fmac_f32_e32 v3, v4, v2
	v_fma_f32 v0, -v1, v3, v0
	v_div_fmas_f32 v0, v0, v2, v3
	v_mov_b64_e32 v[2:3], s[82:83]
	s_movk_i32 s1, 0xc00
	v_mad_i64_i32 v[4:5], s[36:37], v12, s1, v[2:3]
	v_lshrrev_b32_e32 v1, 1, v74
	v_lshl_add_u64 v[4:5], v[4:5], 0, s[30:31]
	v_and_b32_e32 v128, 24, v1
	v_div_fixup_f32 v0, v0, v52, 1.0
	v_lshl_add_u64 v[4:5], v[4:5], 0, v[128:129]
	s_mov_b64 s[38:39], 0xc65c400
	s_mov_b32 s25, 0xc65c000
	v_lshl_add_u64 v[6:7], v[4:5], 0, s[38:39]
	v_pk_mul_f32 v[8:9], v[60:61], v[0:1] op_sel_hi:[1,0]
	v_pk_mul_f32 v[10:11], v[62:63], v[0:1] op_sel_hi:[1,0]
	v_add_co_u32_e32 v4, vcc, s25, v4
	s_waitcnt vmcnt(0)
	v_cvt_pk_bf16_f32 v8, v8, v9
	v_cvt_pk_bf16_f32 v9, v10, v11
	v_addc_co_u32_e32 v5, vcc, 0, v5, vcc
	s_waitcnt lgkmcnt(0)
	s_barrier
	global_store_dwordx2 v[4:5], v[8:9], off offset:1024
	v_pk_mul_f32 v[4:5], v[56:57], v[0:1] op_sel_hi:[1,0]
	v_pk_mul_f32 v[8:9], v[58:59], v[0:1] op_sel_hi:[1,0]
	v_cvt_pk_bf16_f32 v4, v4, v5
	v_cvt_pk_bf16_f32 v5, v8, v9
	global_store_dwordx2 v[6:7], v[4:5], off offset:32
	v_pk_mul_f32 v[4:5], v[48:49], v[0:1] op_sel_hi:[1,0]
	v_pk_mul_f32 v[8:9], v[50:51], v[0:1] op_sel_hi:[1,0]
	v_cvt_pk_bf16_f32 v4, v4, v5
	v_cvt_pk_bf16_f32 v5, v8, v9
	v_div_scale_f32 v8, s[36:37], v36, v36, 1.0
	v_rcp_f32_e32 v9, v8
	global_store_dwordx2 v[6:7], v[4:5], off offset:64
	v_pk_mul_f32 v[4:5], v[40:41], v[0:1] op_sel_hi:[1,0]
	v_pk_mul_f32 v[0:1], v[42:43], v[0:1] op_sel_hi:[1,0]
	v_cvt_pk_bf16_f32 v4, v4, v5
	v_cvt_pk_bf16_f32 v5, v0, v1
	v_fma_f32 v0, -v8, v9, 1.0
	v_fmac_f32_e32 v9, v0, v9
	v_div_scale_f32 v0, vcc, 1.0, v36, 1.0
	v_mul_f32_e32 v1, v0, v9
	global_store_dwordx2 v[6:7], v[4:5], off offset:96
	v_fma_f32 v4, -v8, v1, v0
	v_fmac_f32_e32 v1, v4, v9
	v_fma_f32 v0, -v8, v1, v0
	v_div_fmas_f32 v0, v0, v9, v1
	v_or_b32_e32 v1, 16, v12
	v_mad_i64_i32 v[2:3], s[36:37], v1, s1, v[2:3]
	v_lshl_add_u64 v[2:3], v[2:3], 0, s[30:31]
	v_div_fixup_f32 v0, v0, v36, 1.0
	v_lshl_add_u64 v[2:3], v[2:3], 0, v[128:129]
	v_lshl_add_u64 v[4:5], v[2:3], 0, s[38:39]
	v_pk_mul_f32 v[6:7], v[44:45], v[0:1] op_sel_hi:[1,0]
	v_pk_mul_f32 v[8:9], v[46:47], v[0:1] op_sel_hi:[1,0]
	v_add_co_u32_e32 v2, vcc, s25, v2
	v_cvt_pk_bf16_f32 v6, v6, v7
	v_cvt_pk_bf16_f32 v7, v8, v9
	v_addc_co_u32_e32 v3, vcc, 0, v3, vcc
	global_store_dwordx2 v[2:3], v[6:7], off offset:1024
	v_pk_mul_f32 v[2:3], v[32:33], v[0:1] op_sel_hi:[1,0]
	v_pk_mul_f32 v[6:7], v[34:35], v[0:1] op_sel_hi:[1,0]
	v_cvt_pk_bf16_f32 v2, v2, v3
	v_cvt_pk_bf16_f32 v3, v6, v7
	global_store_dwordx2 v[4:5], v[2:3], off offset:32
	v_pk_mul_f32 v[2:3], v[28:29], v[0:1] op_sel_hi:[1,0]
	v_pk_mul_f32 v[6:7], v[30:31], v[0:1] op_sel_hi:[1,0]
	v_cvt_pk_bf16_f32 v2, v2, v3
	v_cvt_pk_bf16_f32 v3, v6, v7
	global_store_dwordx2 v[4:5], v[2:3], off offset:64
	v_pk_mul_f32 v[2:3], v[24:25], v[0:1] op_sel_hi:[1,0]
	v_pk_mul_f32 v[0:1], v[26:27], v[0:1] op_sel_hi:[1,0]
	s_movk_i32 s84, 0xc00
	v_cvt_pk_bf16_f32 v2, v2, v3
	v_cvt_pk_bf16_f32 v3, v0, v1
	v_readlane_b32 s92, v255, 31
	global_store_dwordx2 v[4:5], v[2:3], off offset:96
	v_readlane_b32 s93, v255, 32
	s_branch .LBB0_108
